# attention tile loop: the per-step barrier moved from the end of the step to the middle of the next one (before the first K-fragment read), so the LDS tile writes drain under the P.V / softmax segment
# speedup vs baseline: 1.0049x; 1.0008x over previous
.Lat_nre:
	s_waitcnt lgkmcnt(0)
	s_barrier
	v_xor_b32_e32 v186, 0x80, v186
	v_xor_b32_e32 v187, 0x80, v187
	v_xor_b32_e32 v188, 0x80, v188
	v_xor_b32_e32 v189, 0x80, v189
	ds_read_b128 v[236:239], v186 offset:49152
	ds_read_b128 v[240:243], v186 offset:57344
	v_cvt_f32_u32_e32 v204, s13
	v_mov_b32_e32 v165, v164
	v_fma_f32 v204, v172, v204, v179
	v_add_f32_e32 v208, v173, v204
	v_add_f32_e32 v212, v173, v208
	v_add_f32_e32 v216, v173, v212
	v_add_f32_e32 v205, v172, v204
	v_add_f32_e32 v209, v172, v208
	v_add_f32_e32 v213, v172, v212
	v_add_f32_e32 v217, v172, v216
	v_pk_add_f32 v[206:207], v[162:163], v[204:205] op_sel_hi:[1,0]
	v_pk_add_f32 v[210:211], v[162:163], v[208:209] op_sel_hi:[1,0]
	v_pk_add_f32 v[214:215], v[162:163], v[212:213] op_sel_hi:[1,0]
	v_pk_add_f32 v[218:219], v[162:163], v[216:217] op_sel_hi:[1,0]
	v_pk_add_f32 v[222:223], v[164:165], v[206:207]
	v_pk_add_f32 v[220:221], v[166:167], v[204:205]
	v_pk_add_f32 v[226:227], v[164:165], v[210:211]
	v_pk_add_f32 v[224:225], v[164:165], v[208:209]
	v_pk_add_f32 v[230:231], v[164:165], v[214:215]
	v_pk_add_f32 v[228:229], v[164:165], v[212:213]
	v_pk_add_f32 v[234:235], v[164:165], v[218:219]
	v_pk_add_f32 v[232:233], v[164:165], v[216:217]
	s_addk_i32 s13, 0x40
	v_exp_f32_e32 v80, v80
	s_waitcnt lgkmcnt(1)
	v_mfma_f32_32x32x16_bf16 v[204:219], v[236:239], v[104:107], v[204:219]
	ds_read_b128 v[236:239], v187 offset:49152
	v_exp_f32_e32 v81, v81
	v_pk_add_f32 v[170:171], v[170:171], v[78:79]
	v_exp_f32_e32 v82, v82
	s_waitcnt lgkmcnt(1)
	v_mfma_f32_32x32x16_bf16 v[220:235], v[240:243], v[104:107], v[220:235]
	ds_read_b128 v[240:243], v187 offset:57344
	v_exp_f32_e32 v83, v83
	v_pk_add_f32 v[170:171], v[170:171], v[80:81]
	v_exp_f32_e32 v84, v84
	v_exp_f32_e32 v85, v85
	s_waitcnt lgkmcnt(1)
	v_mfma_f32_32x32x16_bf16 v[204:219], v[236:239], v[108:111], v[204:219]
	ds_read_b128 v[236:239], v188 offset:49152
	v_pk_add_f32 v[170:171], v[170:171], v[82:83]
	v_exp_f32_e32 v86, v86
	v_exp_f32_e32 v87, v87
	s_waitcnt lgkmcnt(1)
	v_mfma_f32_32x32x16_bf16 v[220:235], v[240:243], v[108:111], v[220:235]
	ds_read_b128 v[240:243], v188 offset:57344
	v_pk_add_f32 v[170:171], v[170:171], v[84:85]
	v_exp_f32_e32 v88, v88
	v_exp_f32_e32 v89, v89
	v_pk_add_f32 v[170:171], v[170:171], v[86:87]
	s_waitcnt lgkmcnt(1)
	v_mfma_f32_32x32x16_bf16 v[204:219], v[236:239], v[112:115], v[204:219]
	ds_read_b128 v[236:239], v189 offset:49152
	v_exp_f32_e32 v90, v90
	v_exp_f32_e32 v91, v91
	v_pk_add_f32 v[170:171], v[170:171], v[88:89]
	v_exp_f32_e32 v92, v92
	s_waitcnt lgkmcnt(1)
	v_mfma_f32_32x32x16_bf16 v[220:235], v[240:243], v[112:115], v[220:235]
	ds_read_b128 v[240:243], v189 offset:57344
	v_exp_f32_e32 v93, v93
	v_pk_add_f32 v[170:171], v[170:171], v[90:91]
	v_exp_f32_e32 v94, v94
	s_waitcnt lgkmcnt(1)
	v_mfma_f32_32x32x16_bf16 v[204:219], v[236:239], v[116:119], v[204:219]
	v_xor_b32_e32 v186, 0x80, v186
	v_xor_b32_e32 v187, 0x80, v187
	v_xor_b32_e32 v188, 0x80, v188
	v_xor_b32_e32 v189, 0x80, v189
	ds_read_b128 v[236:239], v186 offset:49152
	v_exp_f32_e32 v95, v95
	v_pk_add_f32 v[170:171], v[170:171], v[92:93]
	s_nop 0
	v_pk_add_f32 v[170:171], v[170:171], v[94:95]
	s_waitcnt lgkmcnt(1)
	v_mfma_f32_32x32x16_bf16 v[220:235], v[240:243], v[116:119], v[220:235]
	ds_read_b128 v[240:243], v186 offset:57344
	v_add_f32_e32 v249, v170, v171
	v_mov_b32_e32 v170, v249
	s_nop 1
	s_waitcnt lgkmcnt(1)
	v_mfma_f32_32x32x16_bf16 v[204:219], v[236:239], v[120:123], v[204:219]
	ds_read_b128 v[236:239], v187 offset:49152
	v_permlane32_swap_b32_e32 v249, v170
	v_cvt_pk_bf16_f32 v64, v64, v65
	v_cvt_pk_bf16_f32 v65, v66, v67
	v_cvt_pk_bf16_f32 v66, v68, v69
	s_waitcnt lgkmcnt(1)
	v_mfma_f32_32x32x16_bf16 v[220:235], v[240:243], v[120:123], v[220:235]
	ds_read_b128 v[240:243], v187 offset:57344
	v_cvt_pk_bf16_f32 v67, v70, v71
	v_cvt_pk_bf16_f32 v68, v72, v73
	v_cvt_pk_bf16_f32 v69, v74, v75
	s_waitcnt lgkmcnt(1)
	v_mfma_f32_32x32x16_bf16 v[204:219], v[236:239], v[124:127], v[204:219]
	ds_read_b128 v[236:239], v188 offset:49152
	v_cvt_pk_bf16_f32 v70, v76, v77
	v_cvt_pk_bf16_f32 v71, v78, v79
	v_cvt_pk_bf16_f32 v72, v80, v81
	v_cvt_pk_bf16_f32 v73, v82, v83
	s_waitcnt lgkmcnt(1)
	v_mfma_f32_32x32x16_bf16 v[220:235], v[240:243], v[124:127], v[220:235]
	ds_read_b128 v[240:243], v188 offset:57344
	v_cvt_pk_bf16_f32 v74, v84, v85
	v_cvt_pk_bf16_f32 v75, v86, v87
	v_cvt_pk_bf16_f32 v76, v88, v89
	s_waitcnt lgkmcnt(1)
	v_mfma_f32_32x32x16_bf16 v[204:219], v[236:239], v[128:131], v[204:219]
	ds_read_b128 v[236:239], v189 offset:49152
	v_cvt_pk_bf16_f32 v77, v90, v91
	v_cvt_pk_bf16_f32 v78, v92, v93
	v_cvt_pk_bf16_f32 v79, v94, v95
	v_permlane32_swap_b32_e32 v64, v66
	s_waitcnt lgkmcnt(1)
	v_mfma_f32_32x32x16_bf16 v[220:235], v[240:243], v[128:131], v[220:235]
	ds_read_b128 v[240:243], v189 offset:57344
	v_permlane32_swap_b32_e32 v65, v67
	v_permlane32_swap_b32_e32 v68, v70
	v_permlane32_swap_b32_e32 v69, v71
	v_permlane32_swap_b32_e32 v72, v74
	s_waitcnt lgkmcnt(1)
	v_mfma_f32_32x32x16_bf16 v[204:219], v[236:239], v[132:135], v[204:219]
	v_permlane32_swap_b32_e32 v73, v75
	v_permlane32_swap_b32_e32 v76, v78
	v_permlane32_swap_b32_e32 v77, v79
	s_waitcnt lgkmcnt(0)
	v_mfma_f32_32x32x16_bf16 v[220:235], v[240:243], v[132:135], v[220:235]
	v_add_f32_e32 v171, v249, v170
	v_fmac_f32_e32 v171, v185, v202
	v_mov_b32_e32 v185, v171
	s_waitcnt vmcnt(0)
	v_add_u32_e32 v200, s8, v180
	v_add_u32_e32 v201, s8, v181
	ds_write_b128 v200, v[96:99]
	ds_write_b128 v201, v[100:103]
	s_and_b64 vcc, exec, s[34:35]
	s_cbranch_vccz .Lat_nwe
	ds_write_b128 v182, v[136:139] offset:32768
	ds_write_b128 v182, v[140:143] offset:40960
.Lat_nwe:
	s_mov_b32 s9, s6
	s_mov_b32 s6, s7
	s_mov_b32 s7, s8
	s_mov_b32 s8, s9
	s_and_b64 vcc, exec, s[34:35]
	s_cbranch_vccz .Lat_nlo
	global_load_dwordx4 v[96:99], v168, s[22:23]
	global_load_dwordx4 v[100:103], v168, s[20:21]
	global_load_dwordx4 v[136:139], v169, s[42:43]
	global_load_dwordx4 v[140:143], v169, s[26:27]

.Lat_nro:
	s_waitcnt lgkmcnt(0)
	s_barrier
	v_xor_b32_e32 v186, 0x80, v186
	v_xor_b32_e32 v187, 0x80, v187
	v_xor_b32_e32 v188, 0x80, v188
	v_xor_b32_e32 v189, 0x80, v189
	ds_read_b128 v[236:239], v186 offset:32768
	ds_read_b128 v[240:243], v186 offset:40960
	v_cvt_f32_u32_e32 v64, s13
	v_mov_b32_e32 v165, v164
	v_fma_f32 v64, v172, v64, v179
	v_add_f32_e32 v68, v173, v64
	v_add_f32_e32 v72, v173, v68
	v_add_f32_e32 v76, v173, v72
	v_add_f32_e32 v65, v172, v64
	v_add_f32_e32 v69, v172, v68
	v_add_f32_e32 v73, v172, v72
	v_add_f32_e32 v77, v172, v76
	v_pk_add_f32 v[66:67], v[162:163], v[64:65] op_sel_hi:[1,0]
	v_pk_add_f32 v[70:71], v[162:163], v[68:69] op_sel_hi:[1,0]
	v_pk_add_f32 v[74:75], v[162:163], v[72:73] op_sel_hi:[1,0]
	v_pk_add_f32 v[78:79], v[162:163], v[76:77] op_sel_hi:[1,0]
	v_pk_add_f32 v[82:83], v[164:165], v[66:67]
	v_pk_add_f32 v[80:81], v[166:167], v[64:65]
	v_pk_add_f32 v[86:87], v[164:165], v[70:71]
	v_pk_add_f32 v[84:85], v[164:165], v[68:69]
	v_pk_add_f32 v[90:91], v[164:165], v[74:75]
	v_pk_add_f32 v[88:89], v[164:165], v[72:73]
	v_pk_add_f32 v[94:95], v[164:165], v[78:79]
	v_pk_add_f32 v[92:93], v[164:165], v[76:77]
	s_addk_i32 s13, 0x40
	v_exp_f32_e32 v220, v220
	s_waitcnt lgkmcnt(1)
	v_mfma_f32_32x32x16_bf16 v[64:79], v[236:239], v[104:107], v[64:79]
	ds_read_b128 v[236:239], v187 offset:32768
	v_exp_f32_e32 v221, v221
	v_pk_add_f32 v[170:171], v[170:171], v[218:219]
	v_exp_f32_e32 v222, v222
	s_waitcnt lgkmcnt(1)
	v_mfma_f32_32x32x16_bf16 v[80:95], v[240:243], v[104:107], v[80:95]
	ds_read_b128 v[240:243], v187 offset:40960
	v_exp_f32_e32 v223, v223
	v_pk_add_f32 v[170:171], v[170:171], v[220:221]
	v_exp_f32_e32 v224, v224
	v_exp_f32_e32 v225, v225
	s_waitcnt lgkmcnt(1)
	v_mfma_f32_32x32x16_bf16 v[64:79], v[236:239], v[108:111], v[64:79]
	ds_read_b128 v[236:239], v188 offset:32768
	v_pk_add_f32 v[170:171], v[170:171], v[222:223]
	v_exp_f32_e32 v226, v226
	v_exp_f32_e32 v227, v227
	s_waitcnt lgkmcnt(1)
	v_mfma_f32_32x32x16_bf16 v[80:95], v[240:243], v[108:111], v[80:95]
	ds_read_b128 v[240:243], v188 offset:40960
	v_pk_add_f32 v[170:171], v[170:171], v[224:225]
	v_exp_f32_e32 v228, v228
	v_exp_f32_e32 v229, v229
	v_pk_add_f32 v[170:171], v[170:171], v[226:227]
	s_waitcnt lgkmcnt(1)
	v_mfma_f32_32x32x16_bf16 v[64:79], v[236:239], v[112:115], v[64:79]
	ds_read_b128 v[236:239], v189 offset:32768
	v_exp_f32_e32 v230, v230
	v_exp_f32_e32 v231, v231
	v_pk_add_f32 v[170:171], v[170:171], v[228:229]
	v_exp_f32_e32 v232, v232
	s_waitcnt lgkmcnt(1)
	v_mfma_f32_32x32x16_bf16 v[80:95], v[240:243], v[112:115], v[80:95]
	ds_read_b128 v[240:243], v189 offset:40960
	v_exp_f32_e32 v233, v233
	v_pk_add_f32 v[170:171], v[170:171], v[230:231]
	v_exp_f32_e32 v234, v234
	s_waitcnt lgkmcnt(1)
	v_mfma_f32_32x32x16_bf16 v[64:79], v[236:239], v[116:119], v[64:79]
	v_xor_b32_e32 v186, 0x80, v186
	v_xor_b32_e32 v187, 0x80, v187
	v_xor_b32_e32 v188, 0x80, v188
	v_xor_b32_e32 v189, 0x80, v189
	ds_read_b128 v[236:239], v186 offset:32768
	v_exp_f32_e32 v235, v235
	v_pk_add_f32 v[170:171], v[170:171], v[232:233]
	s_nop 0
	v_pk_add_f32 v[170:171], v[170:171], v[234:235]
	s_waitcnt lgkmcnt(1)
	v_mfma_f32_32x32x16_bf16 v[80:95], v[240:243], v[116:119], v[80:95]
	ds_read_b128 v[240:243], v186 offset:40960
	v_add_f32_e32 v249, v170, v171
	v_mov_b32_e32 v170, v249
	s_nop 1
	s_waitcnt lgkmcnt(1)
	v_mfma_f32_32x32x16_bf16 v[64:79], v[236:239], v[120:123], v[64:79]
	ds_read_b128 v[236:239], v187 offset:32768
	v_permlane32_swap_b32_e32 v249, v170
	v_cvt_pk_bf16_f32 v204, v204, v205
	v_cvt_pk_bf16_f32 v205, v206, v207
	v_cvt_pk_bf16_f32 v206, v208, v209
	s_waitcnt lgkmcnt(1)
	v_mfma_f32_32x32x16_bf16 v[80:95], v[240:243], v[120:123], v[80:95]
	ds_read_b128 v[240:243], v187 offset:40960
	v_cvt_pk_bf16_f32 v207, v210, v211
	v_cvt_pk_bf16_f32 v208, v212, v213
	v_cvt_pk_bf16_f32 v209, v214, v215
	s_waitcnt lgkmcnt(1)
	v_mfma_f32_32x32x16_bf16 v[64:79], v[236:239], v[124:127], v[64:79]
	ds_read_b128 v[236:239], v188 offset:32768
	v_cvt_pk_bf16_f32 v210, v216, v217
	v_cvt_pk_bf16_f32 v211, v218, v219
	v_cvt_pk_bf16_f32 v212, v220, v221
	v_cvt_pk_bf16_f32 v213, v222, v223
	s_waitcnt lgkmcnt(1)
	v_mfma_f32_32x32x16_bf16 v[80:95], v[240:243], v[124:127], v[80:95]
	ds_read_b128 v[240:243], v188 offset:40960
	v_cvt_pk_bf16_f32 v214, v224, v225
	v_cvt_pk_bf16_f32 v215, v226, v227
	v_cvt_pk_bf16_f32 v216, v228, v229
	s_waitcnt lgkmcnt(1)
	v_mfma_f32_32x32x16_bf16 v[64:79], v[236:239], v[128:131], v[64:79]
	ds_read_b128 v[236:239], v189 offset:32768
	v_cvt_pk_bf16_f32 v217, v230, v231
	v_cvt_pk_bf16_f32 v218, v232, v233
	v_cvt_pk_bf16_f32 v219, v234, v235
	v_permlane32_swap_b32_e32 v204, v206
	s_waitcnt lgkmcnt(1)
	v_mfma_f32_32x32x16_bf16 v[80:95], v[240:243], v[128:131], v[80:95]
	ds_read_b128 v[240:243], v189 offset:40960
	v_permlane32_swap_b32_e32 v205, v207
	v_permlane32_swap_b32_e32 v208, v210
	v_permlane32_swap_b32_e32 v209, v211
	v_permlane32_swap_b32_e32 v212, v214
	s_waitcnt lgkmcnt(1)
	v_mfma_f32_32x32x16_bf16 v[64:79], v[236:239], v[132:135], v[64:79]
	v_permlane32_swap_b32_e32 v213, v215
	v_permlane32_swap_b32_e32 v216, v218
	v_permlane32_swap_b32_e32 v217, v219
	s_waitcnt lgkmcnt(0)
	v_mfma_f32_32x32x16_bf16 v[80:95], v[240:243], v[132:135], v[80:95]
	v_add_f32_e32 v171, v249, v170
	v_fmac_f32_e32 v171, v185, v202
	v_mov_b32_e32 v185, v171
	s_waitcnt vmcnt(0)
	s_and_b64 vcc, exec, s[34:35]
	s_cbranch_vccz .Lat_nwo
	v_add_u32_e32 v200, s8, v180
	v_add_u32_e32 v201, s8, v181
	ds_write_b128 v200, v[96:99]
	ds_write_b128 v201, v[100:103]
	ds_write_b128 v182, v[136:139] offset:49152
	ds_write_b128 v182, v[140:143] offset:57344
.Lat_nwo:
	s_mov_b32 s9, s6
	s_mov_b32 s6, s7
	s_mov_b32 s7, s8
	s_mov_b32 s8, s9
	s_add_i32 s12, s12, 2
	s_cmp_lt_u32 s12, s18
	s_cbranch_scc1 .Lat_loop
	v_add_u32_e32 v165, s6, v178
	ds_read_b64_tr_b16 v[220:221], v165 offset:0
	ds_read_b64_tr_b16 v[222:223], v165 offset:2048
	ds_read_b64_tr_b16 v[224:225], v165 offset:4096
	ds_read_b64_tr_b16 v[226:227], v165 offset:6144
	ds_read_b64_tr_b16 v[228:229], v165 offset:8192
	ds_read_b64_tr_b16 v[230:231], v165 offset:10240
	ds_read_b64_tr_b16 v[232:233], v165 offset:12288
	ds_read_b64_tr_b16 v[234:235], v165 offset:14336
	s_waitcnt lgkmcnt(0)
	v_mfma_f32_32x32x16_bf16 v[32:47], v[204:207], v[220:223], v[32:47]
	ds_read_b64_tr_b16 v[220:221], v165 offset:512
	ds_read_b64_tr_b16 v[222:223], v165 offset:2560
	v_mfma_f32_32x32x16_bf16 v[32:47], v[208:211], v[224:227], v[32:47]
	ds_read_b64_tr_b16 v[224:225], v165 offset:4608
	ds_read_b64_tr_b16 v[226:227], v165 offset:6656
	v_mfma_f32_32x32x16_bf16 v[32:47], v[212:215], v[228:231], v[32:47]
	ds_read_b64_tr_b16 v[228:229], v165 offset:8704
	ds_read_b64_tr_b16 v[230:231], v165 offset:10752
	v_mfma_f32_32x32x16_bf16 v[32:47], v[216:219], v[232:235], v[32:47]
	ds_read_b64_tr_b16 v[232:233], v165 offset:12800
	ds_read_b64_tr_b16 v[234:235], v165 offset:14848
	s_waitcnt lgkmcnt(0)
	v_mfma_f32_32x32x16_bf16 v[48:63], v[204:207], v[220:223], v[48:63]
	ds_read_b64_tr_b16 v[220:221], v165 offset:1024
	ds_read_b64_tr_b16 v[222:223], v165 offset:3072
	v_mfma_f32_32x32x16_bf16 v[48:63], v[208:211], v[224:227], v[48:63]
	ds_read_b64_tr_b16 v[224:225], v165 offset:5120
	ds_read_b64_tr_b16 v[226:227], v165 offset:7168
	v_mfma_f32_32x32x16_bf16 v[48:63], v[212:215], v[228:231], v[48:63]
	ds_read_b64_tr_b16 v[228:229], v165 offset:9216
	ds_read_b64_tr_b16 v[230:231], v165 offset:11264
	v_mfma_f32_32x32x16_bf16 v[48:63], v[216:219], v[232:235], v[48:63]
	ds_read_b64_tr_b16 v[232:233], v165 offset:13312
	ds_read_b64_tr_b16 v[234:235], v165 offset:15360
	s_waitcnt lgkmcnt(0)
	v_mfma_f32_32x32x16_bf16 v[16:31], v[204:207], v[220:223], v[16:31]
	ds_read_b64_tr_b16 v[220:221], v165 offset:1536
	ds_read_b64_tr_b16 v[222:223], v165 offset:3584
	v_mfma_f32_32x32x16_bf16 v[16:31], v[208:211], v[224:227], v[16:31]
	ds_read_b64_tr_b16 v[224:225], v165 offset:5632
	ds_read_b64_tr_b16 v[226:227], v165 offset:7680
	v_mfma_f32_32x32x16_bf16 v[16:31], v[212:215], v[228:231], v[16:31]
	ds_read_b64_tr_b16 v[228:229], v165 offset:9728
	ds_read_b64_tr_b16 v[230:231], v165 offset:11776
	v_mfma_f32_32x32x16_bf16 v[16:31], v[216:219], v[232:235], v[16:31]
	ds_read_b64_tr_b16 v[232:233], v165 offset:13824
	ds_read_b64_tr_b16 v[234:235], v165 offset:15872
	s_waitcnt lgkmcnt(0)
	v_mfma_f32_32x32x16_bf16 v[0:15], v[204:207], v[220:223], v[0:15]
	v_mfma_f32_32x32x16_bf16 v[0:15], v[208:211], v[224:227], v[0:15]
	v_mfma_f32_32x32x16_bf16 v[0:15], v[212:215], v[228:231], v[0:15]
	v_mfma_f32_32x32x16_bf16 v[0:15], v[216:219], v[232:235], v[0:15]
	s_nop 7
	s_nop 7
